# nt stores for SwiGLU activation only
# baseline (speedup 1.0000x reference)
.LBB0_197:
	v_mul_f32_e32 v160, 0xbfb8aa3b, v126
	v_exp_f32_e32 v160, v160
	v_lshl_or_b32 v162, s21, 7, v144
	v_lshl_add_u32 v146, s20, 8, v142
	v_ashrrev_i32_e32 v163, 31, v162
	v_add_f32_e32 v160, 1.0, v160
	v_rcp_f32_e32 v160, v160
	v_mov_b64_e32 v[140:141], s[8:9]
	v_mad_i64_i32 v[164:165], s[20:21], v146, s64, v[140:141]
	v_mul_f32_e32 v126, v126, v160
	v_mul_f32_e32 v122, v126, v122
	v_mul_f32_e32 v126, 0xbfb8aa3b, v127
	v_exp_f32_e32 v126, v126
	s_andn2_b64 vcc, exec, s[4:5]
	v_add_f32_e32 v126, 1.0, v126
	v_rcp_f32_e32 v126, v126
	s_nop 0
	v_mul_f32_e32 v126, v127, v126
	v_mul_f32_e32 v123, v126, v123
	v_mul_f32_e32 v126, 0xbfb8aa3b, v128
	v_exp_f32_e32 v126, v126
	s_nop 0
	v_add_f32_e32 v126, 1.0, v126
	v_rcp_f32_e32 v126, v126
	s_nop 0
	v_mul_f32_e32 v126, v128, v126
	v_mul_f32_e32 v124, v126, v124
	v_mul_f32_e32 v126, 0xbfb8aa3b, v129
	v_exp_f32_e32 v126, v126
	s_nop 0
	v_add_f32_e32 v126, 1.0, v126
	v_rcp_f32_e32 v126, v126
	s_nop 0
	v_mul_f32_e32 v126, v129, v126
	v_mul_f32_e32 v125, v126, v125
	v_mul_f32_e32 v126, 0xbfb8aa3b, v118
	v_exp_f32_e32 v126, v126
	s_nop 0
	v_add_f32_e32 v126, 1.0, v126
	v_rcp_f32_e32 v126, v126
	s_nop 0
	v_mul_f32_e32 v118, v118, v126
	v_mul_f32_e32 v118, v118, v114
	v_mul_f32_e32 v114, 0xbfb8aa3b, v119
	v_exp_f32_e32 v114, v114
	s_nop 0
	v_add_f32_e32 v114, 1.0, v114
	v_rcp_f32_e32 v114, v114
	s_nop 0
	v_mul_f32_e32 v114, v119, v114
	v_mul_f32_e32 v119, v114, v115
	v_mul_f32_e32 v114, 0xbfb8aa3b, v120
	v_exp_f32_e32 v114, v114
	s_nop 0
	v_add_f32_e32 v114, 1.0, v114
	v_rcp_f32_e32 v114, v114
	s_nop 0
	v_mul_f32_e32 v114, v120, v114
	v_mul_f32_e32 v126, v114, v116
	v_mul_f32_e32 v114, 0xbfb8aa3b, v121
	v_exp_f32_e32 v114, v114
	v_cvt_pk_bf16_f32 v116, v122, v123
	s_nop 0
	v_add_f32_e32 v114, 1.0, v114
	v_rcp_f32_e32 v114, v114
	s_nop 0
	v_mul_f32_e32 v114, v121, v114
	v_mul_f32_e32 v127, v114, v117
	v_lshlrev_b64 v[114:115], 1, v[162:163]
	v_lshl_add_u64 v[120:121], v[164:165], 0, v[114:115]
	v_cvt_pk_bf16_f32 v117, v124, v125
	v_cvt_pk_bf16_f32 v118, v118, v119
	v_cvt_pk_bf16_f32 v119, v126, v127
	global_store_dwordx4 v[120:121], v[116:119], off nt
	s_nop 1
	v_mul_f32_e32 v118, 0xbfb8aa3b, v110
	v_exp_f32_e32 v118, v118
	v_or_b32_e32 v116, 16, v146
	v_mad_i64_i32 v[116:117], s[20:21], v116, s64, v[140:141]
	v_add_f32_e32 v118, 1.0, v118
	v_rcp_f32_e32 v118, v118
	s_nop 0
	v_mul_f32_e32 v110, v110, v118
	v_mul_f32_e32 v106, v110, v106
	v_mul_f32_e32 v110, 0xbfb8aa3b, v111
	v_exp_f32_e32 v110, v110
	s_nop 0
	v_add_f32_e32 v110, 1.0, v110
	v_rcp_f32_e32 v110, v110
	s_nop 0
	v_mul_f32_e32 v110, v111, v110
	v_mul_f32_e32 v107, v110, v107
	v_mul_f32_e32 v110, 0xbfb8aa3b, v112
	v_exp_f32_e32 v110, v110
	s_nop 0
	v_add_f32_e32 v110, 1.0, v110
	v_rcp_f32_e32 v110, v110
	s_nop 0
	v_mul_f32_e32 v110, v112, v110
	v_mul_f32_e32 v108, v110, v108
	v_mul_f32_e32 v110, 0xbfb8aa3b, v113
	v_exp_f32_e32 v110, v110
	s_nop 0
	v_add_f32_e32 v110, 1.0, v110
	v_rcp_f32_e32 v110, v110
	s_nop 0
	v_mul_f32_e32 v110, v113, v110
	v_mul_f32_e32 v109, v110, v109
	v_mul_f32_e32 v110, 0xbfb8aa3b, v102
	v_exp_f32_e32 v110, v110
	s_nop 0
	v_add_f32_e32 v110, 1.0, v110
	v_rcp_f32_e32 v110, v110
	s_nop 0
	v_mul_f32_e32 v102, v102, v110
	v_mul_f32_e32 v110, v102, v98
	v_mul_f32_e32 v98, 0xbfb8aa3b, v103
	v_exp_f32_e32 v98, v98
	s_nop 0
	v_add_f32_e32 v98, 1.0, v98
	v_rcp_f32_e32 v98, v98
	s_nop 0
	v_mul_f32_e32 v98, v103, v98
	v_mul_f32_e32 v111, v98, v99
	v_mul_f32_e32 v98, 0xbfb8aa3b, v104
	v_exp_f32_e32 v98, v98
	v_lshl_add_u64 v[102:103], v[116:117], 0, v[114:115]
	v_add_f32_e32 v98, 1.0, v98
	v_rcp_f32_e32 v98, v98
	s_nop 0
	v_mul_f32_e32 v98, v104, v98
	v_mul_f32_e32 v104, v98, v100
	v_mul_f32_e32 v98, 0xbfb8aa3b, v105
	v_exp_f32_e32 v98, v98
	s_nop 0
	v_add_f32_e32 v98, 1.0, v98
	v_rcp_f32_e32 v98, v98
	s_nop 0
	v_mul_f32_e32 v98, v105, v98
	v_mul_f32_e32 v101, v98, v101
	v_cvt_pk_bf16_f32 v98, v106, v107
	v_cvt_pk_bf16_f32 v99, v108, v109
	v_cvt_pk_bf16_f32 v100, v110, v111
	v_cvt_pk_bf16_f32 v101, v104, v101
	global_store_dwordx4 v[102:103], v[98:101], off nt
	s_nop 1
	v_mul_f32_e32 v100, 0xbfb8aa3b, v94
	v_exp_f32_e32 v100, v100
	v_or_b32_e32 v98, 32, v146
	v_mad_i64_i32 v[98:99], s[20:21], v98, s64, v[140:141]
	v_add_f32_e32 v100, 1.0, v100
	v_rcp_f32_e32 v100, v100
	s_nop 0
	v_mul_f32_e32 v94, v94, v100
	v_mul_f32_e32 v90, v94, v90
	v_mul_f32_e32 v94, 0xbfb8aa3b, v95
	v_exp_f32_e32 v94, v94
	s_nop 0
	v_add_f32_e32 v94, 1.0, v94
	v_rcp_f32_e32 v94, v94
	s_nop 0
	v_mul_f32_e32 v94, v95, v94
	v_mul_f32_e32 v91, v94, v91
	v_mul_f32_e32 v94, 0xbfb8aa3b, v96
	v_exp_f32_e32 v94, v94
	s_nop 0
	v_add_f32_e32 v94, 1.0, v94
	v_rcp_f32_e32 v94, v94
	s_nop 0
	v_mul_f32_e32 v94, v96, v94
	v_mul_f32_e32 v92, v94, v92
	v_mul_f32_e32 v94, 0xbfb8aa3b, v97
	v_exp_f32_e32 v94, v94
	s_nop 0
	v_add_f32_e32 v94, 1.0, v94
	v_rcp_f32_e32 v94, v94
	s_nop 0
	v_mul_f32_e32 v94, v97, v94
	v_mul_f32_e32 v93, v94, v93
	v_mul_f32_e32 v94, 0xbfb8aa3b, v86
	v_exp_f32_e32 v94, v94
	s_nop 0
	v_add_f32_e32 v94, 1.0, v94
	v_rcp_f32_e32 v94, v94
	s_nop 0
	v_mul_f32_e32 v86, v86, v94
	v_mul_f32_e32 v94, v86, v82
	v_mul_f32_e32 v82, 0xbfb8aa3b, v87
	v_exp_f32_e32 v82, v82
	s_nop 0
	v_add_f32_e32 v82, 1.0, v82
	v_rcp_f32_e32 v82, v82
	s_nop 0
	v_mul_f32_e32 v82, v87, v82
	v_mul_f32_e32 v95, v82, v83
	v_mul_f32_e32 v82, 0xbfb8aa3b, v88
	v_exp_f32_e32 v82, v82
	v_lshl_add_u64 v[86:87], v[98:99], 0, v[114:115]
	v_add_f32_e32 v82, 1.0, v82
	v_rcp_f32_e32 v82, v82
	s_nop 0
	v_mul_f32_e32 v82, v88, v82
	v_mul_f32_e32 v88, v82, v84
	v_mul_f32_e32 v82, 0xbfb8aa3b, v89
	v_exp_f32_e32 v82, v82
	s_nop 0
	v_add_f32_e32 v82, 1.0, v82
	v_rcp_f32_e32 v82, v82
	s_nop 0
	v_mul_f32_e32 v82, v89, v82
	v_mul_f32_e32 v85, v82, v85
	v_cvt_pk_bf16_f32 v82, v90, v91
	v_cvt_pk_bf16_f32 v83, v92, v93
	v_cvt_pk_bf16_f32 v84, v94, v95
	v_cvt_pk_bf16_f32 v85, v88, v85
	global_store_dwordx4 v[86:87], v[82:85], off nt
	s_nop 1
	v_mul_f32_e32 v84, 0xbfb8aa3b, v78
	v_exp_f32_e32 v84, v84
	v_or_b32_e32 v82, 48, v146
	v_mad_i64_i32 v[82:83], s[20:21], v82, s64, v[140:141]
	v_add_f32_e32 v84, 1.0, v84
	v_rcp_f32_e32 v84, v84
	s_nop 0
	v_mul_f32_e32 v78, v78, v84
	v_mul_f32_e32 v74, v78, v74
	v_mul_f32_e32 v78, 0xbfb8aa3b, v79
	v_exp_f32_e32 v78, v78
	s_nop 0
	v_add_f32_e32 v78, 1.0, v78
	v_rcp_f32_e32 v78, v78
	s_nop 0
	v_mul_f32_e32 v78, v79, v78
	v_mul_f32_e32 v75, v78, v75
	v_mul_f32_e32 v78, 0xbfb8aa3b, v80
	v_exp_f32_e32 v78, v78
	s_nop 0
	v_add_f32_e32 v78, 1.0, v78
	v_rcp_f32_e32 v78, v78
	s_nop 0
	v_mul_f32_e32 v78, v80, v78
	v_mul_f32_e32 v76, v78, v76
	v_mul_f32_e32 v78, 0xbfb8aa3b, v81
	v_exp_f32_e32 v78, v78
	s_nop 0
	v_add_f32_e32 v78, 1.0, v78
	v_rcp_f32_e32 v78, v78
	s_nop 0
	v_mul_f32_e32 v78, v81, v78
	v_mul_f32_e32 v77, v78, v77
	v_mul_f32_e32 v78, 0xbfb8aa3b, v70
	v_exp_f32_e32 v78, v78
	s_nop 0
	v_add_f32_e32 v78, 1.0, v78
	v_rcp_f32_e32 v78, v78
	s_nop 0
	v_mul_f32_e32 v70, v70, v78
	v_mul_f32_e32 v78, v70, v66
	v_mul_f32_e32 v66, 0xbfb8aa3b, v71
	v_exp_f32_e32 v66, v66
	s_nop 0
	v_add_f32_e32 v66, 1.0, v66
	v_rcp_f32_e32 v66, v66
	s_nop 0
	v_mul_f32_e32 v66, v71, v66
	v_mul_f32_e32 v79, v66, v67
	v_mul_f32_e32 v66, 0xbfb8aa3b, v72
	v_exp_f32_e32 v66, v66
	v_lshl_add_u64 v[70:71], v[82:83], 0, v[114:115]
	v_add_f32_e32 v66, 1.0, v66
	v_rcp_f32_e32 v66, v66
	s_nop 0
	v_mul_f32_e32 v66, v72, v66
	v_mul_f32_e32 v72, v66, v68
	v_mul_f32_e32 v66, 0xbfb8aa3b, v73
	v_exp_f32_e32 v66, v66
	s_nop 0
	v_add_f32_e32 v66, 1.0, v66
	v_rcp_f32_e32 v66, v66
	s_nop 0
	v_mul_f32_e32 v66, v73, v66
	v_mul_f32_e32 v69, v66, v69
	v_cvt_pk_bf16_f32 v66, v74, v75
	v_cvt_pk_bf16_f32 v67, v76, v77
	v_cvt_pk_bf16_f32 v68, v78, v79
	v_cvt_pk_bf16_f32 v69, v72, v69
	global_store_dwordx4 v[70:71], v[66:69], off nt
	s_nop 1
	v_mul_f32_e32 v68, 0xbfb8aa3b, v62
	v_exp_f32_e32 v68, v68
	v_add_u32_e32 v66, 0x80, v146
	v_mad_i64_i32 v[66:67], s[20:21], v66, s64, v[140:141]
	v_add_f32_e32 v68, 1.0, v68
	v_rcp_f32_e32 v68, v68
	s_nop 0
	v_mul_f32_e32 v62, v62, v68
	v_mul_f32_e32 v58, v62, v58
	v_mul_f32_e32 v62, 0xbfb8aa3b, v63
	v_exp_f32_e32 v62, v62
	s_nop 0
	v_add_f32_e32 v62, 1.0, v62
	v_rcp_f32_e32 v62, v62
	s_nop 0
	v_mul_f32_e32 v62, v63, v62
	v_mul_f32_e32 v59, v62, v59
	v_mul_f32_e32 v62, 0xbfb8aa3b, v64
	v_exp_f32_e32 v62, v62
	s_nop 0
	v_add_f32_e32 v62, 1.0, v62
	v_rcp_f32_e32 v62, v62
	s_nop 0
	v_mul_f32_e32 v62, v64, v62
	v_mul_f32_e32 v60, v62, v60
	v_mul_f32_e32 v62, 0xbfb8aa3b, v65
	v_exp_f32_e32 v62, v62
	s_nop 0
	v_add_f32_e32 v62, 1.0, v62
	v_rcp_f32_e32 v62, v62
	s_nop 0
	v_mul_f32_e32 v62, v65, v62
	v_mul_f32_e32 v61, v62, v61
	v_mul_f32_e32 v62, 0xbfb8aa3b, v54
	v_exp_f32_e32 v62, v62
	s_nop 0
	v_add_f32_e32 v62, 1.0, v62
	v_rcp_f32_e32 v62, v62
	s_nop 0
	v_mul_f32_e32 v54, v54, v62
	v_mul_f32_e32 v62, v54, v50
	v_mul_f32_e32 v50, 0xbfb8aa3b, v55
	v_exp_f32_e32 v50, v50
	s_nop 0
	v_add_f32_e32 v50, 1.0, v50
	v_rcp_f32_e32 v50, v50
	s_nop 0
	v_mul_f32_e32 v50, v55, v50
	v_mul_f32_e32 v63, v50, v51
	v_mul_f32_e32 v50, 0xbfb8aa3b, v56
	v_exp_f32_e32 v50, v50
	v_lshl_add_u64 v[54:55], v[66:67], 0, v[114:115]
	v_add_f32_e32 v50, 1.0, v50
	v_rcp_f32_e32 v50, v50
	s_nop 0
	v_mul_f32_e32 v50, v56, v50
	v_mul_f32_e32 v56, v50, v52
	v_mul_f32_e32 v50, 0xbfb8aa3b, v57
	v_exp_f32_e32 v50, v50
	s_nop 0
	v_add_f32_e32 v50, 1.0, v50
	v_rcp_f32_e32 v50, v50
	s_nop 0
	v_mul_f32_e32 v50, v57, v50
	v_mul_f32_e32 v53, v50, v53
	v_cvt_pk_bf16_f32 v50, v58, v59
	v_cvt_pk_bf16_f32 v51, v60, v61
	v_cvt_pk_bf16_f32 v52, v62, v63
	v_cvt_pk_bf16_f32 v53, v56, v53
	global_store_dwordx4 v[54:55], v[50:53], off nt
	s_nop 1
	v_mul_f32_e32 v52, 0xbfb8aa3b, v46
	v_exp_f32_e32 v52, v52
	v_add_u32_e32 v50, 0x90, v146
	v_mad_i64_i32 v[50:51], s[20:21], v50, s64, v[140:141]
	v_add_f32_e32 v52, 1.0, v52
	v_rcp_f32_e32 v52, v52
	s_nop 0
	v_mul_f32_e32 v46, v46, v52
	v_mul_f32_e32 v42, v46, v42
	v_mul_f32_e32 v46, 0xbfb8aa3b, v47
	v_exp_f32_e32 v46, v46
	s_nop 0
	v_add_f32_e32 v46, 1.0, v46
	v_rcp_f32_e32 v46, v46
	s_nop 0
	v_mul_f32_e32 v46, v47, v46
	v_mul_f32_e32 v43, v46, v43
	v_mul_f32_e32 v46, 0xbfb8aa3b, v48
	v_exp_f32_e32 v46, v46
	s_nop 0
	v_add_f32_e32 v46, 1.0, v46
	v_rcp_f32_e32 v46, v46
	s_nop 0
	v_mul_f32_e32 v46, v48, v46
	v_mul_f32_e32 v44, v46, v44
	v_mul_f32_e32 v46, 0xbfb8aa3b, v49
	v_exp_f32_e32 v46, v46
	s_nop 0
	v_add_f32_e32 v46, 1.0, v46
	v_rcp_f32_e32 v46, v46
	s_nop 0
	v_mul_f32_e32 v46, v49, v46
	v_mul_f32_e32 v45, v46, v45
	v_mul_f32_e32 v46, 0xbfb8aa3b, v38
	v_exp_f32_e32 v46, v46
	s_nop 0
	v_add_f32_e32 v46, 1.0, v46
	v_rcp_f32_e32 v46, v46
	s_nop 0
	v_mul_f32_e32 v38, v38, v46
	v_mul_f32_e32 v46, v38, v34
	v_mul_f32_e32 v34, 0xbfb8aa3b, v39
	v_exp_f32_e32 v34, v34
	s_nop 0
	v_add_f32_e32 v34, 1.0, v34
	v_rcp_f32_e32 v34, v34
	s_nop 0
	v_mul_f32_e32 v34, v39, v34
	v_mul_f32_e32 v47, v34, v35
	v_mul_f32_e32 v34, 0xbfb8aa3b, v40
	v_exp_f32_e32 v34, v34
	v_lshl_add_u64 v[38:39], v[50:51], 0, v[114:115]
	v_add_f32_e32 v34, 1.0, v34
	v_rcp_f32_e32 v34, v34
	s_nop 0
	v_mul_f32_e32 v34, v40, v34
	v_mul_f32_e32 v40, v34, v36
	v_mul_f32_e32 v34, 0xbfb8aa3b, v41
	v_exp_f32_e32 v34, v34
	s_nop 0
	v_add_f32_e32 v34, 1.0, v34
	v_rcp_f32_e32 v34, v34
	s_nop 0
	v_mul_f32_e32 v34, v41, v34
	v_mul_f32_e32 v37, v34, v37
	v_cvt_pk_bf16_f32 v34, v42, v43
	v_cvt_pk_bf16_f32 v35, v44, v45
	v_cvt_pk_bf16_f32 v36, v46, v47
	v_cvt_pk_bf16_f32 v37, v40, v37
	global_store_dwordx4 v[38:39], v[34:37], off nt
	s_nop 1
	v_mul_f32_e32 v36, 0xbfb8aa3b, v30
	v_exp_f32_e32 v36, v36
	v_add_u32_e32 v34, 0xa0, v146
	v_mad_i64_i32 v[34:35], s[20:21], v34, s64, v[140:141]
	v_add_f32_e32 v36, 1.0, v36
	v_rcp_f32_e32 v36, v36
	s_nop 0
	v_mul_f32_e32 v30, v30, v36
	v_mul_f32_e32 v26, v30, v26
	v_mul_f32_e32 v30, 0xbfb8aa3b, v31
	v_exp_f32_e32 v30, v30
	s_nop 0
	v_add_f32_e32 v30, 1.0, v30
	v_rcp_f32_e32 v30, v30
	s_nop 0
	v_mul_f32_e32 v30, v31, v30
	v_mul_f32_e32 v27, v30, v27
	v_mul_f32_e32 v30, 0xbfb8aa3b, v32
	v_exp_f32_e32 v30, v30
	s_nop 0
	v_add_f32_e32 v30, 1.0, v30
	v_rcp_f32_e32 v30, v30
	s_nop 0
	v_mul_f32_e32 v30, v32, v30
	v_mul_f32_e32 v28, v30, v28
	v_mul_f32_e32 v30, 0xbfb8aa3b, v33
	v_exp_f32_e32 v30, v30
	s_nop 0
	v_add_f32_e32 v30, 1.0, v30
	v_rcp_f32_e32 v30, v30
	s_nop 0
	v_mul_f32_e32 v30, v33, v30
	v_mul_f32_e32 v29, v30, v29
	v_mul_f32_e32 v30, 0xbfb8aa3b, v22
	v_exp_f32_e32 v30, v30
	s_nop 0
	v_add_f32_e32 v30, 1.0, v30
	v_rcp_f32_e32 v30, v30
	s_nop 0
	v_mul_f32_e32 v22, v22, v30
	v_mul_f32_e32 v30, v22, v18
	v_mul_f32_e32 v18, 0xbfb8aa3b, v23
	v_exp_f32_e32 v18, v18
	s_nop 0
	v_add_f32_e32 v18, 1.0, v18
	v_rcp_f32_e32 v18, v18
	s_nop 0
	v_mul_f32_e32 v18, v23, v18
	v_mul_f32_e32 v31, v18, v19
	v_mul_f32_e32 v18, 0xbfb8aa3b, v24
	v_exp_f32_e32 v18, v18
	v_lshl_add_u64 v[22:23], v[34:35], 0, v[114:115]
	v_add_f32_e32 v18, 1.0, v18
	v_rcp_f32_e32 v18, v18
	s_nop 0
	v_mul_f32_e32 v18, v24, v18
	v_mul_f32_e32 v24, v18, v20
	v_mul_f32_e32 v18, 0xbfb8aa3b, v25
	v_exp_f32_e32 v18, v18
	s_nop 0
	v_add_f32_e32 v18, 1.0, v18
	v_rcp_f32_e32 v18, v18
	s_nop 0
	v_mul_f32_e32 v18, v25, v18
	v_mul_f32_e32 v21, v18, v21
	v_cvt_pk_bf16_f32 v18, v26, v27
	v_cvt_pk_bf16_f32 v19, v28, v29
	v_cvt_pk_bf16_f32 v20, v30, v31
	v_cvt_pk_bf16_f32 v21, v24, v21
	global_store_dwordx4 v[22:23], v[18:21], off nt
	s_nop 1
	v_mul_f32_e32 v20, 0xbfb8aa3b, v14
	v_exp_f32_e32 v20, v20
	v_add_u32_e32 v18, 0xb0, v146
	v_mad_i64_i32 v[18:19], s[20:21], v18, s64, v[140:141]
	v_add_f32_e32 v20, 1.0, v20
	v_rcp_f32_e32 v20, v20
	s_mov_b64 s[20:21], -1
	v_mul_f32_e32 v14, v14, v20
	v_mul_f32_e32 v10, v14, v10
	v_mul_f32_e32 v14, 0xbfb8aa3b, v15
	v_exp_f32_e32 v14, v14
	s_nop 0
	v_add_f32_e32 v14, 1.0, v14
	v_rcp_f32_e32 v14, v14
	s_nop 0
	v_mul_f32_e32 v14, v15, v14
	v_mul_f32_e32 v11, v14, v11
	v_mul_f32_e32 v14, 0xbfb8aa3b, v16
	v_exp_f32_e32 v14, v14
	s_nop 0
	v_add_f32_e32 v14, 1.0, v14
	v_rcp_f32_e32 v14, v14
	s_nop 0
	v_mul_f32_e32 v14, v16, v14
	v_mul_f32_e32 v12, v14, v12
	v_mul_f32_e32 v14, 0xbfb8aa3b, v17
	v_exp_f32_e32 v14, v14
	s_nop 0
	v_add_f32_e32 v14, 1.0, v14
	v_rcp_f32_e32 v14, v14
	s_nop 0
	v_mul_f32_e32 v14, v17, v14
	v_mul_f32_e32 v13, v14, v13
	v_mul_f32_e32 v14, 0xbfb8aa3b, v6
	v_exp_f32_e32 v14, v14
	s_nop 0
	v_add_f32_e32 v14, 1.0, v14
	v_rcp_f32_e32 v14, v14
	s_nop 0
	v_mul_f32_e32 v6, v6, v14
	v_mul_f32_e32 v14, v6, v2
	v_mul_f32_e32 v2, 0xbfb8aa3b, v7
	v_exp_f32_e32 v2, v2
	s_nop 0
	v_add_f32_e32 v2, 1.0, v2
	v_rcp_f32_e32 v2, v2
	s_nop 0
	v_mul_f32_e32 v2, v7, v2
	v_mul_f32_e32 v15, v2, v3
	v_mul_f32_e32 v2, 0xbfb8aa3b, v8
	v_exp_f32_e32 v2, v2
	v_lshl_add_u64 v[6:7], v[18:19], 0, v[114:115]
	v_add_f32_e32 v2, 1.0, v2
	v_rcp_f32_e32 v2, v2
	s_nop 0
	v_mul_f32_e32 v2, v8, v2
	v_mul_f32_e32 v8, v2, v4
	v_mul_f32_e32 v2, 0xbfb8aa3b, v9
	v_exp_f32_e32 v2, v2
	s_nop 0
	v_add_f32_e32 v2, 1.0, v2
	v_rcp_f32_e32 v2, v2
	s_nop 0
	v_mul_f32_e32 v2, v9, v2
	v_mul_f32_e32 v5, v2, v5
	v_cvt_pk_bf16_f32 v2, v10, v11
	v_cvt_pk_bf16_f32 v3, v12, v13
	v_cvt_pk_bf16_f32 v4, v14, v15
	v_cvt_pk_bf16_f32 v5, v8, v5
	global_store_dwordx4 v[6:7], v[2:5], off nt
	s_cbranch_vccnz .LBB0_190
	s_andn2_b64 vcc, exec, s[6:7]
	s_cbranch_vccnz .LBB0_189
	s_barrier
	s_branch .LBB0_189
